# P0 wf staging loads batched; P1 mem-kv WGs take 5 proj tiles, WGs 160-191 take 7
# speedup vs baseline: 1.0090x; 1.0090x over previous
; #define LAS __attribute__((address_space(3)))
; __device__ __forceinline__ void p0_prologue(Frame& F) {
;     LAS float* scr = (LAS float*)(F.lds + F.wave * 8448);
;     LAS float* wf = (LAS float*)(F.lds + 8 * 8448);
;     for (int i = F.tid; i < D * 8; i += NTHREADS) wf[i] = F.w_in[(size_t)(i >> 3) * DIN + 3072 + (i & 7)];
.LBB0_15:
	v_lshrrev_b32_e32 v198, 3, v0
	v_and_b32_e32 v199, 7, v0
	v_mul_u32_u24_e32 v198, 0x6820, v198
	v_lshl_add_u32 v198, v199, 2, v198
	v_add_u32_e32 v198, 0x3000, v198
	s_mov_b64 s[6:7], s[44:45]
	global_load_dword v200, v198, s[6:7]
	s_add_u32 s6, s6, 0x1a0800
	s_addc_u32 s7, s7, 0
	global_load_dword v201, v198, s[6:7]
	s_add_u32 s6, s6, 0x1a0800
	s_addc_u32 s7, s7, 0
	global_load_dword v202, v198, s[6:7]
	s_add_u32 s6, s6, 0x1a0800
	s_addc_u32 s7, s7, 0
	global_load_dword v203, v198, s[6:7]
	s_add_u32 s6, s6, 0x1a0800
	s_addc_u32 s7, s7, 0
	global_load_dword v204, v198, s[6:7]
	s_add_u32 s6, s6, 0x1a0800
	s_addc_u32 s7, s7, 0
	global_load_dword v205, v198, s[6:7]
	s_add_u32 s6, s6, 0x1a0800
	s_addc_u32 s7, s7, 0
	global_load_dword v206, v198, s[6:7]
	s_add_u32 s6, s6, 0x1a0800
	s_addc_u32 s7, s7, 0
	global_load_dword v207, v198, s[6:7]
	s_add_u32 s6, s6, 0x1a0800
	s_addc_u32 s7, s7, 0
	global_load_dword v208, v198, s[6:7]
	s_add_u32 s6, s6, 0x1a0800
	s_addc_u32 s7, s7, 0
	global_load_dword v209, v198, s[6:7]
	s_add_u32 s6, s6, 0x1a0800
	s_addc_u32 s7, s7, 0
	global_load_dword v210, v198, s[6:7]
	s_add_u32 s6, s6, 0x1a0800
	s_addc_u32 s7, s7, 0
	global_load_dword v211, v198, s[6:7]
	s_add_u32 s6, s6, 0x1a0800
	s_addc_u32 s7, s7, 0
	global_load_dword v212, v198, s[6:7]
	s_add_u32 s6, s6, 0x1a0800
	s_addc_u32 s7, s7, 0
	global_load_dword v213, v198, s[6:7]
	s_add_u32 s6, s6, 0x1a0800
	s_addc_u32 s7, s7, 0
	global_load_dword v214, v198, s[6:7]
	s_add_u32 s6, s6, 0x1a0800
	s_addc_u32 s7, s7, 0
	global_load_dword v215, v198, s[6:7]
	v_lshlrev_b32_e32 v199, 2, v0
	v_add_u32_e32 v199, 0x10800, v199
	s_or_b64 exec, exec, s[0:1]
	v_cmp_eq_u32_e64 s[2:3], 2, 0
	s_and_saveexec_b64 s[0:1], s[2:3]
	s_cbranch_execz .LBB0_18
	v_readlane_b32 s36, v247, 2
	v_readlane_b32 s44, v247, 10
	v_readlane_b32 s45, v247, 11
	v_lshrrev_b32_e32 v1, 3, v7
	v_lshrrev_b32_e32 v3, 3, v6
	s_movk_i32 s4, 0x6820
	v_mov_b64_e32 v[6:7], s[44:45]
	v_mad_u64_u32 v[8:9], s[2:3], v3, s4, v[6:7]
	v_mov_b32_e32 v5, 0
	v_mad_u64_u32 v[6:7], s[2:3], v1, s4, v[6:7]
	v_lshl_add_u64 v[8:9], v[8:9], 0, v[4:5]
	v_lshl_add_u64 v[4:5], v[6:7], 0, v[4:5]
	v_add_co_u32_e32 v6, vcc, 0x3000, v8
	v_readlane_b32 s37, v247, 3
	s_nop 0
	v_addc_co_u32_e32 v7, vcc, 0, v9, vcc
	v_add_co_u32_e32 v4, vcc, 0x3000, v4
	v_readlane_b32 s38, v247, 4
	s_nop 0
	v_addc_co_u32_e32 v5, vcc, 0, v5, vcc
	global_load_dword v1, v[6:7], off
	global_load_dword v3, v[4:5], off
	v_lshl_or_b32 v4, 16, 11, v10
	v_add_u32_e32 v4, 0, v4
	v_add_u32_e32 v4, 0x10800, v4
	v_readlane_b32 s39, v247, 5
	v_readlane_b32 s40, v247, 6
	v_readlane_b32 s41, v247, 7
	v_readlane_b32 s42, v247, 8
	v_readlane_b32 s43, v247, 9
	v_readlane_b32 s46, v247, 12
	v_readlane_b32 s47, v247, 13
	v_readlane_b32 s48, v247, 14
	v_readlane_b32 s49, v247, 15
	v_readlane_b32 s50, v247, 16
	v_readlane_b32 s51, v247, 17
	s_waitcnt vmcnt(0)
	ds_write2st64_b32 v4, v1, v3 offset1:8

; #define GAS __attribute__((address_space(1)))
; template <bool IS_X>
; __device__ __forceinline__ void p0_rows(Frame& F, const float* srcb, const float* g, bf16* dstb, int nrows, const LAS float* wf, int gw, int NGW) {
;     const GAS f32x4* gr = (const GAS f32x4*)g + F.lane;
;     f32x4 wfr[4][4][2];
;     if (IS_X) {
; #pragma unroll
;         for (int j = 0; j < 4; ++j)
; #pragma unroll
;             for (int e = 0; e < 4; ++e) { const LAS f32x4* wp = (const LAS f32x4*)(wf + (256 * j + 4 * F.lane + e) * 8); wfr[j][e][0] = wp[0]; wfr[j][e][1] = wp[1]; } }
;     f32x4 nx[4];
;     if (gw < nrows) { const GAS f32x4* xr = (const GAS f32x4*)(srcb + (size_t)gw * D) + F.lane;
; #pragma unroll
;         for (int j = 0; j < 4; ++j) nx[j] = IS_X ? xr[64 * j] : __builtin_nontemporal_load(xr + 64 * j);     }
;     for (int m = gw; m < nrows; m += NGW) {
;         f32x4 v[4]; float s = 0.f;
; #pragma unroll
;         for (int j = 0; j < 4; ++j) v[j] = nx[j];
;         if (m + NGW < nrows) { const GAS f32x4* xr = (const GAS f32x4*)(srcb + (size_t)(m + NGW) * D) + F.lane;
; #pragma unroll
;             for (int j = 0; j < 4; ++j) nx[j] = IS_X ? xr[64 * j] : __builtin_nontemporal_load(xr + 64 * j);     }
; #pragma unroll
;         for (int j = 0; j < 4; ++j) s += (v[j].x * v[j].x + v[j].y * v[j].y) + (v[j].z * v[j].z + v[j].w * v[j].w);
;         const float rstd = __builtin_amdgcn_rsqf(wave_sum(s) * (1.f / D) + EPS);
; #pragma unroll
;         for (int j = 0; j < 4; ++j) { const f32x4 gg = gr[64 * j]; v[j] = v[j] * rstd * gg; }
;         GAS unsigned long long* o8 = (GAS unsigned long long*)(dstb + (size_t)m * D) + F.lane;
; #pragma unroll
;         for (int j = 0; j < 4; ++j) o8[64 * j] = (unsigned long long)pk2(v[j].x, v[j].y) | ((unsigned long long)pk2(v[j].z, v[j].w) << 32);
;         if (IS_X) {
;             float fl[8];
; #pragma unroll
;             for (int c = 0; c < 8; ++c) fl[c] = 0.f;
; #pragma unroll
;             for (int j = 0; j < 4; ++j)
; #pragma unroll
;                 for (int e = 0; e < 4; ++e) { const float hv = v[j][e]; const f32x4 w0 = wfr[j][e][0], w1 = wfr[j][e][1];
;                     fl[0] += hv * w0.x; fl[1] += hv * w0.y; fl[2] += hv * w0.z; fl[3] += hv * w0.w; fl[4] += hv * w1.x; fl[5] += hv * w1.y; fl[6] += hv * w1.z; fl[7] += hv * w1.w; }
;             float mine = 0.f;
; #pragma unroll
.LBB0_88:
	v_mov_b32_e32 v163, 0
	s_cmpk_gt_i32 s0, 0x3fff
	v_lshlrev_b32_e32 v162, 4, v178
	s_waitcnt vmcnt(8)
	ds_write_b32 v199, v200 offset:0
	ds_write_b32 v199, v201 offset:2048
	ds_write_b32 v199, v202 offset:4096
	ds_write_b32 v199, v203 offset:6144
	ds_write_b32 v199, v204 offset:8192
	ds_write_b32 v199, v205 offset:10240
	ds_write_b32 v199, v206 offset:12288
	ds_write_b32 v199, v207 offset:14336
	ds_write_b32 v199, v208 offset:16384
	ds_write_b32 v199, v209 offset:18432
	ds_write_b32 v199, v210 offset:20480
	ds_write_b32 v199, v211 offset:22528
	ds_write_b32 v199, v212 offset:24576
	ds_write_b32 v199, v213 offset:26624
	ds_write_b32 v199, v214 offset:28672
	ds_write_b32 v199, v215 offset:30720
	s_waitcnt lgkmcnt(0)
	s_barrier
	s_cbranch_scc1 .LBB0_96
	v_readlane_b32 s4, v247, 2
	v_readlane_b32 s10, v247, 8
	v_readlane_b32 s11, v247, 9
	v_readlane_b32 s5, v247, 3
	v_readlane_b32 s6, v247, 4
	v_readlane_b32 s7, v247, 5
	v_readlane_b32 s8, v247, 6
	v_readlane_b32 s9, v247, 7
	s_mov_b64 s[78:79], s[10:11]
	s_ashr_i32 s1, s0, 31
	s_mov_b64 s[72:73], s[4:5]
	s_lshl_b64 s[2:3], s[0:1], 12
	v_lshl_add_u32 v1, v178, 7, 0
	s_add_u32 s2, s72, s2
	v_add_u32_e32 v126, 0x10800, v1
	s_addc_u32 s3, s73, s3
	ds_read_b128 v[2:5], v126 offset:24688
	ds_read_b128 v[6:9], v126 offset:24672
	ds_read_b128 v[10:13], v126 offset:24656
	ds_read_b128 v[14:17], v126 offset:24640
	ds_read_b128 v[18:21], v126 offset:24624
	ds_read_b128 v[22:25], v126 offset:24608
	ds_read_b128 v[26:29], v126 offset:24592
	ds_read_b128 v[30:33], v126 offset:24576
	ds_read_b128 v[34:37], v126 offset:16496
	ds_read_b128 v[38:41], v126 offset:16480
	ds_read_b128 v[42:45], v126 offset:16464
	ds_read_b128 v[46:49], v126 offset:16448
	ds_read_b128 v[50:53], v126 offset:16432
	ds_read_b128 v[54:57], v126 offset:16416
	ds_read_b128 v[58:61], v126 offset:16400
	ds_read_b128 v[62:65], v126 offset:16384
	global_load_dwordx4 v[146:149], v162, s[2:3] offset:3072
	global_load_dwordx4 v[150:153], v162, s[2:3] offset:2048
	global_load_dwordx4 v[154:157], v162, s[2:3] offset:1024
	global_load_dwordx4 v[158:161], v162, s[2:3]
	v_mbcnt_lo_u32_b32 v1, -1, 0
	v_mbcnt_hi_u32_b32 v66, -1, v1
	v_and_b32_e32 v1, 64, v66
	v_add_u32_e32 v67, 64, v1
	v_xor_b32_e32 v1, 1, v66
	v_cmp_lt_i32_e32 vcc, v1, v67
	v_xor_b32_e32 v68, 2, v66
	v_readlane_b32 s14, v247, 12
	v_cndmask_b32_e32 v1, v66, v1, vcc
	v_cmp_lt_i32_e32 vcc, v68, v67
	v_readlane_b32 s15, v247, 13
	s_mov_b64 s[82:83], s[14:15]
	v_cndmask_b32_e32 v68, v66, v68, vcc
	v_lshlrev_b32_e32 v179, 2, v68
	v_xor_b32_e32 v68, 4, v66
	v_cmp_lt_i32_e32 vcc, v68, v67
	s_lshl_b64 s[2:3], s[0:1], 5
	s_add_i32 s28, s0, s24
	v_cndmask_b32_e32 v68, v66, v68, vcc
	v_lshlrev_b32_e32 v180, 2, v68
	v_xor_b32_e32 v68, 8, v66
	v_cmp_lt_i32_e32 vcc, v68, v67
	s_ashr_i32 s25, s24, 31
	s_lshl_b64 s[26:27], s[0:1], 11
	v_cndmask_b32_e32 v68, v66, v68, vcc
	v_lshlrev_b32_e32 v181, 2, v68
	v_xor_b32_e32 v68, 16, v66
	v_cmp_lt_i32_e32 vcc, v68, v67
	s_ashr_i32 s29, s28, 31
	v_lshl_or_b32 v170, v178, 3, s26
	v_cndmask_b32_e32 v68, v66, v68, vcc
	v_lshlrev_b32_e32 v182, 2, v68
	v_xor_b32_e32 v68, 32, v66
	v_cmp_lt_i32_e32 vcc, v68, v67
	v_mov_b32_e32 v67, v163
	v_mov_b32_e32 v171, s27
	v_cndmask_b32_e32 v66, v66, v68, vcc
	v_lshlrev_b32_e32 v183, 2, v66
	v_lshlrev_b32_e32 v66, 2, v178
	v_lshl_add_u64 v[166:167], s[82:83], 0, v[66:67]
	v_lshl_add_u64 v[66:67], s[2:3], 0, v[66:67]
	s_mov_b64 s[2:3], 0x100000
	v_lshl_add_u64 v[168:169], v[66:67], 0, s[2:3]
	s_lshl_b64 s[2:3], s[24:25], 5
	s_lshl_b64 s[26:27], s[24:25], 11
	s_lshl_b64 s[28:29], s[28:29], 12
	s_add_u32 s28, s72, s28
	s_addc_u32 s29, s73, s29
	v_lshl_add_u64 v[66:67], s[28:29], 0, v[162:163]
	s_mov_b64 s[28:29], 0x800
	v_lshl_add_u64 v[172:173], v[66:67], 0, s[28:29]
	ds_read_b128 v[66:69], v126 offset:8304
	ds_read_b128 v[70:73], v126 offset:8288
	ds_read_b128 v[74:77], v126 offset:8272
	ds_read_b128 v[78:81], v126 offset:8256
	ds_read_b128 v[82:85], v126 offset:8240
	ds_read_b128 v[86:89], v126 offset:8224
	ds_read_b128 v[90:93], v126 offset:8208
	ds_read_b128 v[94:97], v126 offset:8192
	ds_read_b128 v[98:101], v126 offset:112
	ds_read_b128 v[102:105], v126 offset:96
	ds_read_b128 v[106:109], v126 offset:80
	ds_read_b128 v[110:113], v126 offset:64
	ds_read_b128 v[114:117], v126
	ds_read_b128 v[118:121], v126 offset:16
	ds_read_b128 v[122:125], v126 offset:32
	ds_read_b128 v[126:129], v126 offset:48
	v_readlane_b32 s12, v247, 10
	v_readlane_b32 s13, v247, 11
	v_readlane_b32 s16, v247, 14
	v_readlane_b32 s17, v247, 15
	v_readlane_b32 s18, v247, 16
	v_readlane_b32 s19, v247, 17
	s_mov_b64 s[76:77], s[8:9]
	s_mov_b64 s[74:75], s[6:7]
	v_lshl_add_u64 v[164:165], s[76:77], 0, v[162:163]
	v_lshlrev_b32_e32 v1, 2, v1
	v_cmp_gt_u32_e64 s[20:21], 8, v178
	v_cmp_eq_u32_e64 s[4:5], 7, v178
	v_cmp_eq_u32_e64 s[6:7], 6, v178
	v_cmp_eq_u32_e64 s[8:9], 5, v178
	v_cmp_eq_u32_e64 s[10:11], 4, v178
	v_cmp_eq_u32_e64 s[12:13], 3, v178
	v_cmp_eq_u32_e64 s[14:15], 2, v178
	v_cmp_eq_u32_e64 s[16:17], 1, v178
	v_cmp_eq_u32_e64 s[18:19], 0, v178
	s_lshl_b64 s[28:29], s[24:25], 12
	v_mov_b32_e32 v163, 0x358637bd
	s_movk_i32 s1, 0x7fff
	s_mov_b32 s25, 0xffff0000
	s_waitcnt vmcnt(3)
	v_mov_b64_e32 v[130:131], v[146:147]
	s_waitcnt vmcnt(2)
	v_mov_b64_e32 v[134:135], v[150:151]
	s_waitcnt vmcnt(1)
	v_mov_b64_e32 v[138:139], v[154:155]
	s_waitcnt vmcnt(0)
	v_mov_b64_e32 v[142:143], v[158:159]
	s_mov_b32 s33, 0x2c00000
	s_mov_b32 s36, 0xbfb8aa3b
	s_mov_b32 s37, 0xb2a5705f
	s_mov_b32 s38, 0x42ce8ed0
	s_mov_b32 s39, 0xc2b17218
	s_mov_b32 s40, 0x7f800000
	s_mov_b32 s41, 0x3f2aaaab
	v_mov_b32_e32 v184, 0x3ecc95a3
	s_mov_b32 s42, 0x3f317218
	s_mov_b32 s43, 0x33800000
	v_mov_b32_e32 v185, 0x7f800000
	v_mov_b32_e32 v174, 0x3f317218
	s_mov_b32 s44, s0
	v_mov_b64_e32 v[132:133], v[148:149]
	v_mov_b64_e32 v[136:137], v[152:153]
	v_mov_b64_e32 v[140:141], v[156:157]
	v_mov_b64_e32 v[144:145], v[160:161]
	s_branch .LBB0_91

;     __device__ __forceinline__ bool next(int i, Unit& u) const { const long L = (long)i * G + c; if (L >= (long)nM * nN) return false; static_tile((int)L, nM, nN, u.pm, u.pn); u.br = 0; return true; }
;     __device__ __forceinline__ bool next(int i, Unit& u) const { if (i >= 1 || c >= 256) return false; static_tile(c, 64, 4, u.pm, u.pn); u.br = br; return true; }
;     __device__ __forceinline__ bool next(int i, Unit& u) const { if (i >= 3 || c >= 256) return false; static_tile(c, 64, 4, u.pm, u.pn); u.br = i; return true; }
;     __device__ __forceinline__ bool next(int i, Unit& u) const {
;         if (G == 256 && c >= 128 && c < 160) { if (i == 0) { const int j = c - 128; u.pm = 64 + (j & 7); u.pn = 26 + (j >> 3); u.br = 0; return true; }
;             if (i > 6) return false; static_tile((i - 1) * G + c, 64, 26, u.pm, u.pn); u.br = 0; return true; }
;         const long L = (long)i * G + c; if (L >= 1696) return false;
;         if (L < 1664) static_tile((int)L, 64, 26, u.pm, u.pn); else { const int r = (int)L - 1664; u.pm = 64 + (r >> 2); u.pn = 26 + (r & 3); } u.br = 0; return true; }
.LBB0_174:
	s_mul_i32 s3, s70, s80
	s_mul_hi_i32 s2, s70, s80
	s_add_u32 s14, s3, s90
	s_addc_u32 s15, s2, s62
	s_add_i32 s2, s14, 0xfffff960
	s_cmp_lt_u32 s2, 32
	s_cselect_b32 s2, 0x120, 0
	s_sub_u32 s14, s14, s2
	s_subb_u32 s15, s15, 0
	v_cmp_gt_i64_e32 vcc, s[14:15], v[166:167]
	s_mov_b64 s[2:3], 0
	s_mov_b64 s[28:29], 0
	s_mov_b32 s10, s11
	s_mov_b32 s12, s8
	s_cbranch_vccnz .LBB0_180
	v_cmp_gt_i64_e32 vcc, s[14:15], v[168:169]
	s_mov_b64 s[16:17], -1
	s_cbranch_vccz .LBB0_177
	s_add_i32 s10, s14, 0xfffff980
	s_lshr_b32 s10, s10, 2
	s_and_b32 s12, s14, 3
	s_add_i32 s10, s10, 64
	s_add_i32 s12, s12, 26
	s_mov_b64 s[16:17], 0

;     __device__ __forceinline__ bool next(int i, Unit& u) const {
;         if (G == 256 && c >= 128 && c < 160) { if (i == 0) { const int j = c - 128; u.pm = 64 + (j & 7); u.pn = 26 + (j >> 3); u.br = 0; return true; }
;             if (i > 6) return false; static_tile((i - 1) * G + c, 64, 26, u.pm, u.pn); u.br = 0; return true; }
.LBB0_180:
	s_andn2_b64 vcc, exec, s[2:3]
	s_cbranch_vccnz .LBB0_186
	s_cmp_eq_u32 s70, 0
	s_cbranch_scc1 .LBB0_184
	s_cmp_gt_i32 s7, 4
	s_mov_b64 s[28:29], 0
	s_cbranch_scc1 .LBB0_185
	s_lshl_b32 s2, s70, 8
	s_add_i32 s2, s2, s61
	s_ashr_i32 s3, s2, 31
	s_lshr_b32 s3, s3, 29
	s_add_i32 s3, s2, s3
	s_ashr_i32 s8, s3, 3
	s_and_b32 s3, s3, -8
	s_sub_i32 s2, s2, s3
	s_cmp_lt_i32 s2, 0
	s_cselect_b32 s3, s65, 0xd0
	s_mul_i32 s2, s3, s2
	s_add_i32 s2, s2, s8
	s_mul_hi_i32 s3, s2, 0x4ec4ec4f
	s_lshr_b32 s8, s3, 31
	s_ashr_i32 s3, s3, 5
	s_add_i32 s3, s3, s8
	s_lshl_b32 s10, s3, 2
	s_sub_i32 s8, 64, s10
	s_min_i32 s11, s8, 4
	s_abs_i32 s8, s11
	v_cvt_f32_u32_e32 v130, s8
	s_sub_i32 s13, 0, s8
	s_mulk_i32 s3, 0x68
	s_sub_i32 s2, s2, s3
	v_rcp_iflag_f32_e32 v130, v130
	s_abs_i32 s3, s2
	s_xor_b32 s12, s2, s11
	s_ashr_i32 s12, s12, 31
	v_mul_f32_e32 v130, 0x4f7ffffe, v130
	v_cvt_u32_f32_e32 v130, v130
	s_mov_b64 s[28:29], -1
	v_readfirstlane_b32 s14, v130
	s_mul_i32 s13, s13, s14
	s_mul_hi_u32 s13, s14, s13
	s_add_i32 s14, s14, s13
	s_mul_hi_u32 s13, s3, s14
	s_mul_i32 s14, s13, s8
	s_sub_i32 s3, s3, s14
	s_add_i32 s15, s13, 1
	s_sub_i32 s14, s3, s8
	s_cmp_ge_u32 s3, s8
	s_cselect_b32 s13, s15, s13
	s_cselect_b32 s3, s14, s3
	s_add_i32 s14, s13, 1
	s_cmp_ge_u32 s3, s8
	s_cselect_b32 s3, s14, s13
	s_xor_b32 s3, s3, s12
	s_sub_i32 s8, s3, s12
	s_mul_i32 s3, s8, s11
	s_sub_i32 s2, s2, s3
	s_add_i32 s11, s2, s10
	s_branch .LBB0_185
